# GEMM k-loops: one static s_setprio 1 for waves 4-7 (the half one phase behind), per-segment priority toggles removed
# speedup vs baseline: 1.0045x; 1.0045x over previous
.LBB0_821:
	s_ashr_i32 s41, s40, 31
	s_lshl_b64 s[34:35], s[40:41], 20
	s_add_u32 s42, s12, s34
	s_addc_u32 s43, s13, s35
	s_and_b64 s[34:35], s[36:37], exec
	s_cselect_b32 s41, s43, s31
	s_cselect_b32 s54, s42, s30
	s_ashr_i32 s39, s38, 31
	s_lshl_b64 s[34:35], s[38:39], 20
	s_add_u32 s44, s83, s34
	s_addc_u32 s45, s80, s35
	s_and_b64 s[34:35], s[36:37], exec
	s_cselect_b32 s39, s45, s25
	s_cselect_b32 s55, s44, s24
	s_add_u32 s30, s30, 0x80080
	s_addc_u32 s31, s31, 0
	s_add_u32 s56, s24, 0x100
	v_mov_b32_e32 v0, 0
	s_addc_u32 s57, s25, 0
	s_mov_b32 s58, -2
	v_mov_b32_e32 v1, v0
	v_mov_b32_e32 v2, v0
	v_mov_b32_e32 v3, v0
	v_mov_b32_e32 v4, v0
	v_mov_b32_e32 v5, v0
	v_mov_b32_e32 v6, v0
	v_mov_b32_e32 v7, v0
	v_mov_b32_e32 v16, v0
	v_mov_b32_e32 v17, v0
	v_mov_b32_e32 v18, v0
	v_mov_b32_e32 v19, v0
	v_mov_b32_e32 v20, v0
	v_mov_b32_e32 v21, v0
	v_mov_b32_e32 v22, v0
	v_mov_b32_e32 v23, v0
	v_mov_b32_e32 v40, v0
	v_mov_b32_e32 v41, v0
	v_mov_b32_e32 v42, v0
	v_mov_b32_e32 v43, v0
	v_mov_b32_e32 v44, v0
	v_mov_b32_e32 v45, v0
	v_mov_b32_e32 v46, v0
	v_mov_b32_e32 v47, v0
	v_mov_b32_e32 v56, v0
	v_mov_b32_e32 v57, v0
	v_mov_b32_e32 v58, v0
	v_mov_b32_e32 v59, v0
	v_mov_b32_e32 v60, v0
	v_mov_b32_e32 v61, v0
	v_mov_b32_e32 v62, v0
	v_mov_b32_e32 v63, v0
	v_mov_b32_e32 v8, v0
	v_mov_b32_e32 v9, v0
	v_mov_b32_e32 v10, v0
	v_mov_b32_e32 v11, v0
	v_mov_b32_e32 v12, v0
	v_mov_b32_e32 v13, v0
	v_mov_b32_e32 v14, v0
	v_mov_b32_e32 v15, v0
	v_mov_b32_e32 v24, v0
	v_mov_b32_e32 v25, v0
	v_mov_b32_e32 v26, v0
	v_mov_b32_e32 v27, v0
	v_mov_b32_e32 v28, v0
	v_mov_b32_e32 v29, v0
	v_mov_b32_e32 v30, v0
	v_mov_b32_e32 v31, v0
	v_mov_b32_e32 v48, v0
	v_mov_b32_e32 v49, v0
	v_mov_b32_e32 v50, v0
	v_mov_b32_e32 v51, v0
	v_mov_b32_e32 v52, v0
	v_mov_b32_e32 v53, v0
	v_mov_b32_e32 v54, v0
	v_mov_b32_e32 v55, v0
	v_mov_b32_e32 v64, v0
	v_mov_b32_e32 v65, v0
	v_mov_b32_e32 v66, v0
	v_mov_b32_e32 v67, v0
	v_mov_b32_e32 v68, v0
	v_mov_b32_e32 v69, v0
	v_mov_b32_e32 v70, v0
	v_mov_b32_e32 v71, v0
	v_mov_b32_e32 v72, v0
	v_mov_b32_e32 v73, v0
	v_mov_b32_e32 v74, v0
	v_mov_b32_e32 v75, v0
	v_mov_b32_e32 v76, v0
	v_mov_b32_e32 v77, v0
	v_mov_b32_e32 v78, v0
	v_mov_b32_e32 v79, v0
	s_waitcnt vmcnt(0)
	v_mov_b32_e32 v88, v0
	v_mov_b32_e32 v89, v0
	v_mov_b32_e32 v90, v0
	v_mov_b32_e32 v91, v0
	v_mov_b32_e32 v92, v0
	v_mov_b32_e32 v93, v0
	v_mov_b32_e32 v94, v0
	v_mov_b32_e32 v95, v0
	v_mov_b32_e32 v104, v0
	v_mov_b32_e32 v105, v0
	v_mov_b32_e32 v106, v0
	v_mov_b32_e32 v107, v0
	v_mov_b32_e32 v108, v0
	v_mov_b32_e32 v109, v0
	v_mov_b32_e32 v110, v0
	v_mov_b32_e32 v111, v0
	v_mov_b32_e32 v120, v0
	v_mov_b32_e32 v121, v0
	v_mov_b32_e32 v122, v0
	v_mov_b32_e32 v123, v0
	v_mov_b32_e32 v124, v0
	v_mov_b32_e32 v125, v0
	v_mov_b32_e32 v126, v0
	v_mov_b32_e32 v127, v0
	v_mov_b32_e32 v80, v0
	v_mov_b32_e32 v81, v0
	v_mov_b32_e32 v82, v0
	v_mov_b32_e32 v83, v0
	v_mov_b32_e32 v84, v0
	v_mov_b32_e32 v85, v0
	v_mov_b32_e32 v86, v0
	v_mov_b32_e32 v87, v0
	v_mov_b32_e32 v96, v0
	v_mov_b32_e32 v97, v0
	v_mov_b32_e32 v98, v0
	v_mov_b32_e32 v99, v0
	v_mov_b32_e32 v100, v0
	v_mov_b32_e32 v101, v0
	v_mov_b32_e32 v102, v0
	v_mov_b32_e32 v103, v0
	v_mov_b32_e32 v112, v0
	v_mov_b32_e32 v113, v0
	v_mov_b32_e32 v114, v0
	v_mov_b32_e32 v115, v0
	v_mov_b32_e32 v116, v0
	v_mov_b32_e32 v117, v0
	v_mov_b32_e32 v118, v0
	v_mov_b32_e32 v119, v0
	v_mov_b32_e32 v128, v0
	v_mov_b32_e32 v129, v0
	v_mov_b32_e32 v130, v0
	v_mov_b32_e32 v131, v0
	v_mov_b32_e32 v132, v0
	v_mov_b32_e32 v133, v0
	v_mov_b32_e32 v134, v0
	v_mov_b32_e32 v135, v0
	v_readfirstlane_b32 s98, v165
	s_lshr_b32 s98, s98, 8
	s_cmp_eq_u32 s98, 1
	s_cbranch_scc0 .Lprio_skip0
	s_setprio 1
.Lprio_skip0:
.LBB0_822:
	s_add_u32 s24, s30, 0xfff80080
	s_addc_u32 s25, s31, -1
	s_add_i32 s26, 0, 0x10000
	s_cmp_eq_u32 s58, 28
	s_cselect_b32 s35, s41, s25
	s_cselect_b32 s34, s54, s24
	v_add_u32_e32 v140, s26, v155
	s_cselect_b32 s25, s39, s57
	s_cselect_b32 s24, s55, s56
	s_add_i32 s59, 0, 0x14000
	ds_read_b128 v[136:139], v140
	ds_read_b128 v[158:161], v140 offset:1024
	ds_read_b128 v[172:175], v140 offset:2048
	ds_read_b128 v[192:195], v140 offset:3072
	v_add_u32_e32 v140, s59, v155
	ds_read_b128 v[196:199], v140
	ds_read_b128 v[200:203], v140 offset:1024
	ds_read_b128 v[204:207], v140 offset:2048
	ds_read_b128 v[208:211], v140 offset:3072
	v_lshl_add_u64 v[140:141], s[30:31], 0, v[150:151]
	s_add_i32 m0, s29, 0xc000
	ds_read_b128 v[212:215], v163
	ds_read_b128 v[216:219], v163 offset:1024
	ds_read_b128 v[220:223], v163 offset:2048
	ds_read_b128 v[224:227], v163 offset:3072
	ds_read_b128 v[228:231], v163 offset:4096
	ds_read_b128 v[232:235], v163 offset:5120
	ds_read_b128 v[236:239], v163 offset:6144
	ds_read_b128 v[240:243], v163 offset:7168
	global_load_lds_dwordx4 v[140:141], off
	v_lshl_add_u64 v[140:141], s[30:31], 0, v[152:153]
	s_add_i32 m0, s29, 0xe000
	s_nop 0
	global_load_lds_dwordx4 v[140:141], off
	s_waitcnt vmcnt(8)
	s_waitcnt lgkmcnt(0)
	s_barrier
	s_waitcnt lgkmcnt(0)
	v_mfma_f32_16x16x32_bf16 v[132:135], v[136:139], v[212:215], v[132:135]
	v_mfma_f32_16x16x32_bf16 v[128:131], v[172:175], v[212:215], v[128:131]
	v_mfma_f32_16x16x32_bf16 v[116:119], v[136:139], v[220:223], v[116:119]
	v_mfma_f32_16x16x32_bf16 v[112:115], v[172:175], v[220:223], v[112:115]
	v_mfma_f32_16x16x32_bf16 v[100:103], v[136:139], v[228:231], v[100:103]
	v_mfma_f32_16x16x32_bf16 v[96:99], v[172:175], v[228:231], v[96:99]
	v_mfma_f32_16x16x32_bf16 v[84:87], v[136:139], v[236:239], v[84:87]
	v_mfma_f32_16x16x32_bf16 v[80:83], v[172:175], v[236:239], v[80:83]
	v_mfma_f32_16x16x32_bf16 v[132:135], v[158:161], v[216:219], v[132:135]
	v_mfma_f32_16x16x32_bf16 v[128:131], v[192:195], v[216:219], v[128:131]
	v_mfma_f32_16x16x32_bf16 v[116:119], v[158:161], v[224:227], v[116:119]
	v_mfma_f32_16x16x32_bf16 v[112:115], v[192:195], v[224:227], v[112:115]
	v_mfma_f32_16x16x32_bf16 v[100:103], v[158:161], v[232:235], v[100:103]
	v_mfma_f32_16x16x32_bf16 v[96:99], v[192:195], v[232:235], v[96:99]
	v_mfma_f32_16x16x32_bf16 v[84:87], v[158:161], v[240:243], v[84:87]
	v_mfma_f32_16x16x32_bf16 v[80:83], v[192:195], v[240:243], v[80:83]
	v_mfma_f32_16x16x32_bf16 v[124:127], v[196:199], v[212:215], v[124:127]
	v_mfma_f32_16x16x32_bf16 v[120:123], v[204:207], v[212:215], v[120:123]
	v_mfma_f32_16x16x32_bf16 v[108:111], v[196:199], v[220:223], v[108:111]
	v_mfma_f32_16x16x32_bf16 v[104:107], v[204:207], v[220:223], v[104:107]
	v_mfma_f32_16x16x32_bf16 v[92:95], v[196:199], v[228:231], v[92:95]
	v_mfma_f32_16x16x32_bf16 v[88:91], v[204:207], v[228:231], v[88:91]
	v_mfma_f32_16x16x32_bf16 v[76:79], v[196:199], v[236:239], v[76:79]
	v_mfma_f32_16x16x32_bf16 v[72:75], v[204:207], v[236:239], v[72:75]
	v_mfma_f32_16x16x32_bf16 v[124:127], v[200:203], v[216:219], v[124:127]
	v_mfma_f32_16x16x32_bf16 v[120:123], v[208:211], v[216:219], v[120:123]
	v_mfma_f32_16x16x32_bf16 v[108:111], v[200:203], v[224:227], v[108:111]
	v_mfma_f32_16x16x32_bf16 v[104:107], v[208:211], v[224:227], v[104:107]
	v_mfma_f32_16x16x32_bf16 v[92:95], v[200:203], v[232:235], v[92:95]
	v_mfma_f32_16x16x32_bf16 v[88:91], v[208:211], v[232:235], v[88:91]
	v_mfma_f32_16x16x32_bf16 v[76:79], v[200:203], v[240:243], v[76:79]
	v_mfma_f32_16x16x32_bf16 v[72:75], v[208:211], v[240:243], v[72:75]
	s_barrier
	s_add_i32 s26, s26, s22
	v_lshl_add_u64 v[140:141], s[24:25], 0, v[146:147]
	s_mov_b32 m0, s26
	ds_read_b128 v[212:215], v163 offset:16384
	ds_read_b128 v[216:219], v163 offset:17408
	ds_read_b128 v[220:223], v163 offset:18432
	ds_read_b128 v[224:227], v163 offset:19456
	ds_read_b128 v[228:231], v163 offset:20480
	ds_read_b128 v[232:235], v163 offset:21504
	ds_read_b128 v[236:239], v163 offset:22528
	ds_read_b128 v[240:243], v163 offset:23552
	global_load_lds_dwordx4 v[140:141], off
	s_add_i32 m0, s26, 0x2000
	s_add_u32 s68, s24, 0x80000
	v_lshl_add_u64 v[142:143], s[24:25], 0, v[34:35]
	s_addc_u32 s69, s25, 0
	s_add_i32 s26, s59, s22
	global_load_lds_dwordx4 v[142:143], off
	v_lshl_add_u64 v[168:169], s[68:69], 0, v[146:147]
	s_mov_b32 m0, s26
	v_lshl_add_u64 v[176:177], s[34:35], 0, v[144:145]
	global_load_lds_dwordx4 v[168:169], off
	v_lshl_add_u64 v[168:169], s[68:69], 0, v[34:35]
	s_add_i32 m0, s26, 0x2000
	s_nop 0
	global_load_lds_dwordx4 v[168:169], off
	v_lshl_add_u64 v[168:169], s[34:35], 0, v[148:149]
	s_mov_b32 m0, s29
	s_nop 0
	global_load_lds_dwordx4 v[168:169], off
	s_mov_b32 m0, s47
	s_nop 0
	global_load_lds_dwordx4 v[176:177], off
	s_waitcnt vmcnt(8)
	s_waitcnt lgkmcnt(0)
	s_barrier
	s_waitcnt lgkmcnt(0)
	v_mfma_f32_16x16x32_bf16 v[68:71], v[136:139], v[212:215], v[68:71]
	v_mfma_f32_16x16x32_bf16 v[64:67], v[172:175], v[212:215], v[64:67]
	v_mfma_f32_16x16x32_bf16 v[52:55], v[136:139], v[220:223], v[52:55]
	v_mfma_f32_16x16x32_bf16 v[48:51], v[172:175], v[220:223], v[48:51]
	v_mfma_f32_16x16x32_bf16 v[28:31], v[136:139], v[228:231], v[28:31]
	v_mfma_f32_16x16x32_bf16 v[24:27], v[172:175], v[228:231], v[24:27]
	v_mfma_f32_16x16x32_bf16 v[12:15], v[136:139], v[236:239], v[12:15]
	v_mfma_f32_16x16x32_bf16 v[8:11], v[172:175], v[236:239], v[8:11]
	v_mfma_f32_16x16x32_bf16 v[68:71], v[158:161], v[216:219], v[68:71]
	v_mfma_f32_16x16x32_bf16 v[64:67], v[192:195], v[216:219], v[64:67]
	v_mfma_f32_16x16x32_bf16 v[52:55], v[158:161], v[224:227], v[52:55]
	v_mfma_f32_16x16x32_bf16 v[48:51], v[192:195], v[224:227], v[48:51]
	v_mfma_f32_16x16x32_bf16 v[28:31], v[158:161], v[232:235], v[28:31]
	v_mfma_f32_16x16x32_bf16 v[24:27], v[192:195], v[232:235], v[24:27]
	v_mfma_f32_16x16x32_bf16 v[12:15], v[158:161], v[240:243], v[12:15]
	v_mfma_f32_16x16x32_bf16 v[8:11], v[192:195], v[240:243], v[8:11]
	v_mfma_f32_16x16x32_bf16 v[60:63], v[196:199], v[212:215], v[60:63]
	v_mfma_f32_16x16x32_bf16 v[56:59], v[204:207], v[212:215], v[56:59]
	v_mfma_f32_16x16x32_bf16 v[44:47], v[196:199], v[220:223], v[44:47]
	v_mfma_f32_16x16x32_bf16 v[40:43], v[204:207], v[220:223], v[40:43]
	v_mfma_f32_16x16x32_bf16 v[20:23], v[196:199], v[228:231], v[20:23]
	v_mfma_f32_16x16x32_bf16 v[16:19], v[204:207], v[228:231], v[16:19]
	v_mfma_f32_16x16x32_bf16 v[4:7], v[196:199], v[236:239], v[4:7]
	v_mfma_f32_16x16x32_bf16 v[0:3], v[204:207], v[236:239], v[0:3]
	v_mfma_f32_16x16x32_bf16 v[60:63], v[200:203], v[216:219], v[60:63]
	v_mfma_f32_16x16x32_bf16 v[56:59], v[208:211], v[216:219], v[56:59]
	v_mfma_f32_16x16x32_bf16 v[44:47], v[200:203], v[224:227], v[44:47]
	v_mfma_f32_16x16x32_bf16 v[40:43], v[208:211], v[224:227], v[40:43]
	v_mfma_f32_16x16x32_bf16 v[20:23], v[200:203], v[232:235], v[20:23]
	v_mfma_f32_16x16x32_bf16 v[16:19], v[208:211], v[232:235], v[16:19]
	v_mfma_f32_16x16x32_bf16 v[4:7], v[200:203], v[240:243], v[4:7]
	v_mfma_f32_16x16x32_bf16 v[0:3], v[208:211], v[240:243], v[0:3]
	s_barrier
	s_add_i32 s26, 0, 0x18000
	v_add_u32_e32 v154, s26, v155
	s_add_i32 s59, 0, 0x1c000
	ds_read_b128 v[136:139], v154
	ds_read_b128 v[158:161], v154 offset:1024
	ds_read_b128 v[172:175], v154 offset:2048
	ds_read_b128 v[192:195], v154 offset:3072
	v_add_u32_e32 v154, s59, v155
	ds_read_b128 v[196:199], v154
	ds_read_b128 v[200:203], v154 offset:1024
	ds_read_b128 v[204:207], v154 offset:2048
	ds_read_b128 v[208:211], v154 offset:3072
	s_add_u32 s34, s34, 0x80000
	s_addc_u32 s35, s35, 0
	s_mov_b32 m0, s48
	v_lshl_add_u64 v[244:245], s[34:35], 0, v[148:149]
	ds_read_b128 v[212:215], v163 offset:32768
	ds_read_b128 v[216:219], v163 offset:33792
	ds_read_b128 v[220:223], v163 offset:34816
	ds_read_b128 v[224:227], v163 offset:35840
	ds_read_b128 v[228:231], v163 offset:36864
	ds_read_b128 v[232:235], v163 offset:37888
	ds_read_b128 v[236:239], v163 offset:38912
	ds_read_b128 v[240:243], v163 offset:39936
	global_load_lds_dwordx4 v[244:245], off
	v_lshl_add_u64 v[244:245], s[34:35], 0, v[144:145]
	s_mov_b32 m0, s49
	s_nop 0
	global_load_lds_dwordx4 v[244:245], off
	s_waitcnt vmcnt(8)
	s_waitcnt lgkmcnt(0)
	s_barrier
	s_waitcnt lgkmcnt(0)
	v_mfma_f32_16x16x32_bf16 v[132:135], v[136:139], v[212:215], v[132:135]
	v_mfma_f32_16x16x32_bf16 v[128:131], v[172:175], v[212:215], v[128:131]
	v_mfma_f32_16x16x32_bf16 v[116:119], v[136:139], v[220:223], v[116:119]
	v_mfma_f32_16x16x32_bf16 v[112:115], v[172:175], v[220:223], v[112:115]
	v_mfma_f32_16x16x32_bf16 v[100:103], v[136:139], v[228:231], v[100:103]
	v_mfma_f32_16x16x32_bf16 v[96:99], v[172:175], v[228:231], v[96:99]
	v_mfma_f32_16x16x32_bf16 v[84:87], v[136:139], v[236:239], v[84:87]
	v_mfma_f32_16x16x32_bf16 v[80:83], v[172:175], v[236:239], v[80:83]
	v_mfma_f32_16x16x32_bf16 v[132:135], v[158:161], v[216:219], v[132:135]
	v_mfma_f32_16x16x32_bf16 v[128:131], v[192:195], v[216:219], v[128:131]
	v_mfma_f32_16x16x32_bf16 v[116:119], v[158:161], v[224:227], v[116:119]
	v_mfma_f32_16x16x32_bf16 v[112:115], v[192:195], v[224:227], v[112:115]
	v_mfma_f32_16x16x32_bf16 v[100:103], v[158:161], v[232:235], v[100:103]
	v_mfma_f32_16x16x32_bf16 v[96:99], v[192:195], v[232:235], v[96:99]
	v_mfma_f32_16x16x32_bf16 v[84:87], v[158:161], v[240:243], v[84:87]
	v_mfma_f32_16x16x32_bf16 v[80:83], v[192:195], v[240:243], v[80:83]
	v_mfma_f32_16x16x32_bf16 v[124:127], v[196:199], v[212:215], v[124:127]
	v_mfma_f32_16x16x32_bf16 v[120:123], v[204:207], v[212:215], v[120:123]
	v_mfma_f32_16x16x32_bf16 v[108:111], v[196:199], v[220:223], v[108:111]
	v_mfma_f32_16x16x32_bf16 v[104:107], v[204:207], v[220:223], v[104:107]
	v_mfma_f32_16x16x32_bf16 v[92:95], v[196:199], v[228:231], v[92:95]
	v_mfma_f32_16x16x32_bf16 v[88:91], v[204:207], v[228:231], v[88:91]
	v_mfma_f32_16x16x32_bf16 v[76:79], v[196:199], v[236:239], v[76:79]
	v_mfma_f32_16x16x32_bf16 v[72:75], v[204:207], v[236:239], v[72:75]
	v_mfma_f32_16x16x32_bf16 v[124:127], v[200:203], v[216:219], v[124:127]
	v_mfma_f32_16x16x32_bf16 v[120:123], v[208:211], v[216:219], v[120:123]
	v_mfma_f32_16x16x32_bf16 v[108:111], v[200:203], v[224:227], v[108:111]
	v_mfma_f32_16x16x32_bf16 v[104:107], v[208:211], v[224:227], v[104:107]
	v_mfma_f32_16x16x32_bf16 v[92:95], v[200:203], v[232:235], v[92:95]
	v_mfma_f32_16x16x32_bf16 v[88:91], v[208:211], v[232:235], v[88:91]
	v_mfma_f32_16x16x32_bf16 v[76:79], v[200:203], v[240:243], v[76:79]
	v_mfma_f32_16x16x32_bf16 v[72:75], v[208:211], v[240:243], v[72:75]
	s_barrier
	s_add_i32 s26, s26, s22
	v_lshl_add_u64 v[140:141], v[140:141], 0, s[60:61]
	s_mov_b32 m0, s26
	ds_read_b128 v[212:215], v163 offset:49152
	ds_read_b128 v[216:219], v163 offset:50176
	ds_read_b128 v[220:223], v163 offset:51200
	ds_read_b128 v[224:227], v163 offset:52224
	ds_read_b128 v[228:231], v163 offset:53248
	ds_read_b128 v[232:235], v163 offset:54272
	ds_read_b128 v[236:239], v163 offset:55296
	ds_read_b128 v[240:243], v163 offset:56320
	global_load_lds_dwordx4 v[140:141], off
	s_add_i32 m0, s26, 0x2000
	s_add_u32 s24, s24, 0x80080
	v_lshl_add_u64 v[140:141], v[142:143], 0, s[60:61]
	s_addc_u32 s25, s25, 0
	s_add_i32 s26, s59, s22
	global_load_lds_dwordx4 v[140:141], off
	v_lshl_add_u64 v[140:141], s[24:25], 0, v[146:147]
	s_mov_b32 m0, s26
	s_nop 0
	global_load_lds_dwordx4 v[140:141], off
	v_lshl_add_u64 v[140:141], s[24:25], 0, v[34:35]
	s_add_i32 m0, s26, 0x2000
	s_nop 0
	global_load_lds_dwordx4 v[140:141], off
	v_lshl_add_u64 v[140:141], v[168:169], 0, s[60:61]
	s_mov_b32 m0, s50
	s_nop 0
	global_load_lds_dwordx4 v[140:141], off
	v_lshl_add_u64 v[140:141], v[176:177], 0, s[60:61]
	s_mov_b32 m0, s51
	s_nop 0
	global_load_lds_dwordx4 v[140:141], off
	s_waitcnt vmcnt(8)
	s_waitcnt lgkmcnt(0)
	s_barrier
	s_waitcnt lgkmcnt(0)
	v_mfma_f32_16x16x32_bf16 v[68:71], v[136:139], v[212:215], v[68:71]
	v_mfma_f32_16x16x32_bf16 v[64:67], v[172:175], v[212:215], v[64:67]
	v_mfma_f32_16x16x32_bf16 v[52:55], v[136:139], v[220:223], v[52:55]
	v_mfma_f32_16x16x32_bf16 v[48:51], v[172:175], v[220:223], v[48:51]
	v_mfma_f32_16x16x32_bf16 v[28:31], v[136:139], v[228:231], v[28:31]
	v_mfma_f32_16x16x32_bf16 v[24:27], v[172:175], v[228:231], v[24:27]
	v_mfma_f32_16x16x32_bf16 v[12:15], v[136:139], v[236:239], v[12:15]
	v_mfma_f32_16x16x32_bf16 v[8:11], v[172:175], v[236:239], v[8:11]
	v_mfma_f32_16x16x32_bf16 v[68:71], v[158:161], v[216:219], v[68:71]
	v_mfma_f32_16x16x32_bf16 v[64:67], v[192:195], v[216:219], v[64:67]
	v_mfma_f32_16x16x32_bf16 v[52:55], v[158:161], v[224:227], v[52:55]
	v_mfma_f32_16x16x32_bf16 v[48:51], v[192:195], v[224:227], v[48:51]
	v_mfma_f32_16x16x32_bf16 v[28:31], v[158:161], v[232:235], v[28:31]
	v_mfma_f32_16x16x32_bf16 v[24:27], v[192:195], v[232:235], v[24:27]
	v_mfma_f32_16x16x32_bf16 v[12:15], v[158:161], v[240:243], v[12:15]
	v_mfma_f32_16x16x32_bf16 v[8:11], v[192:195], v[240:243], v[8:11]
	v_mfma_f32_16x16x32_bf16 v[60:63], v[196:199], v[212:215], v[60:63]
	v_mfma_f32_16x16x32_bf16 v[56:59], v[204:207], v[212:215], v[56:59]
	v_mfma_f32_16x16x32_bf16 v[44:47], v[196:199], v[220:223], v[44:47]
	v_mfma_f32_16x16x32_bf16 v[40:43], v[204:207], v[220:223], v[40:43]
	v_mfma_f32_16x16x32_bf16 v[20:23], v[196:199], v[228:231], v[20:23]
	v_mfma_f32_16x16x32_bf16 v[16:19], v[204:207], v[228:231], v[16:19]
	v_mfma_f32_16x16x32_bf16 v[4:7], v[196:199], v[236:239], v[4:7]
	v_mfma_f32_16x16x32_bf16 v[0:3], v[204:207], v[236:239], v[0:3]
	v_mfma_f32_16x16x32_bf16 v[60:63], v[200:203], v[216:219], v[60:63]
	v_mfma_f32_16x16x32_bf16 v[56:59], v[208:211], v[216:219], v[56:59]
	v_mfma_f32_16x16x32_bf16 v[44:47], v[200:203], v[224:227], v[44:47]
	v_mfma_f32_16x16x32_bf16 v[40:43], v[208:211], v[224:227], v[40:43]
	v_mfma_f32_16x16x32_bf16 v[20:23], v[200:203], v[232:235], v[20:23]
	v_mfma_f32_16x16x32_bf16 v[16:19], v[208:211], v[232:235], v[16:19]
	v_mfma_f32_16x16x32_bf16 v[4:7], v[200:203], v[240:243], v[4:7]
	v_mfma_f32_16x16x32_bf16 v[0:3], v[208:211], v[240:243], v[0:3]
	s_barrier
	s_add_i32 s58, s58, 2
	s_add_u32 s30, s30, 0x100
	s_addc_u32 s31, s31, 0
	s_add_u32 s56, s56, 0x100
	s_addc_u32 s57, s57, 0
	s_cmp_gt_u32 s58, 29
	s_cbranch_scc0 .LBB0_822
	s_setprio 0
	s_and_b64 vcc, exec, s[2:3]
	s_cbranch_vccz .LBB0_825
	s_barrier

.LBB0_853:
	s_add_u32 s28, s28, 0x80
	s_addc_u32 s29, s29, 0
	s_add_u32 s30, s24, 0x100
	v_mov_b32_e32 v0, 0
	s_addc_u32 s31, s25, 0
	s_mov_b32 s24, 0
	v_mov_b32_e32 v1, v0
	v_mov_b32_e32 v2, v0
	v_mov_b32_e32 v3, v0
	v_mov_b32_e32 v4, v0
	v_mov_b32_e32 v5, v0
	v_mov_b32_e32 v6, v0
	v_mov_b32_e32 v7, v0
	v_mov_b32_e32 v16, v0
	v_mov_b32_e32 v17, v0
	v_mov_b32_e32 v18, v0
	v_mov_b32_e32 v19, v0
	v_mov_b32_e32 v20, v0
	v_mov_b32_e32 v21, v0
	v_mov_b32_e32 v22, v0
	v_mov_b32_e32 v23, v0
	v_mov_b32_e32 v40, v0
	v_mov_b32_e32 v41, v0
	v_mov_b32_e32 v42, v0
	v_mov_b32_e32 v43, v0
	v_mov_b32_e32 v44, v0
	v_mov_b32_e32 v45, v0
	v_mov_b32_e32 v46, v0
	v_mov_b32_e32 v47, v0
	v_mov_b32_e32 v56, v0
	v_mov_b32_e32 v57, v0
	v_mov_b32_e32 v58, v0
	v_mov_b32_e32 v59, v0
	v_mov_b32_e32 v60, v0
	v_mov_b32_e32 v61, v0
	v_mov_b32_e32 v62, v0
	v_mov_b32_e32 v63, v0
	v_mov_b32_e32 v8, v0
	v_mov_b32_e32 v9, v0
	v_mov_b32_e32 v10, v0
	v_mov_b32_e32 v11, v0
	v_mov_b32_e32 v12, v0
	v_mov_b32_e32 v13, v0
	v_mov_b32_e32 v14, v0
	v_mov_b32_e32 v15, v0
	v_mov_b32_e32 v24, v0
	v_mov_b32_e32 v25, v0
	v_mov_b32_e32 v26, v0
	v_mov_b32_e32 v27, v0
	v_mov_b32_e32 v28, v0
	v_mov_b32_e32 v29, v0
	v_mov_b32_e32 v30, v0
	v_mov_b32_e32 v31, v0
	v_mov_b32_e32 v48, v0
	v_mov_b32_e32 v49, v0
	v_mov_b32_e32 v50, v0
	v_mov_b32_e32 v51, v0
	v_mov_b32_e32 v52, v0
	v_mov_b32_e32 v53, v0
	v_mov_b32_e32 v54, v0
	v_mov_b32_e32 v55, v0
	v_mov_b32_e32 v64, v0
	v_mov_b32_e32 v65, v0
	v_mov_b32_e32 v66, v0
	v_mov_b32_e32 v67, v0
	v_mov_b32_e32 v68, v0
	v_mov_b32_e32 v69, v0
	v_mov_b32_e32 v70, v0
	v_mov_b32_e32 v71, v0
	v_mov_b32_e32 v72, v0
	v_mov_b32_e32 v73, v0
	v_mov_b32_e32 v74, v0
	v_mov_b32_e32 v75, v0
	v_mov_b32_e32 v76, v0
	v_mov_b32_e32 v77, v0
	v_mov_b32_e32 v78, v0
	v_mov_b32_e32 v79, v0
	s_waitcnt vmcnt(0)
	v_mov_b32_e32 v88, v0
	v_mov_b32_e32 v89, v0
	v_mov_b32_e32 v90, v0
	v_mov_b32_e32 v91, v0
	v_mov_b32_e32 v92, v0
	v_mov_b32_e32 v93, v0
	v_mov_b32_e32 v94, v0
	v_mov_b32_e32 v95, v0
	v_mov_b32_e32 v104, v0
	v_mov_b32_e32 v105, v0
	v_mov_b32_e32 v106, v0
	v_mov_b32_e32 v107, v0
	v_mov_b32_e32 v108, v0
	v_mov_b32_e32 v109, v0
	v_mov_b32_e32 v110, v0
	v_mov_b32_e32 v111, v0
	v_mov_b32_e32 v120, v0
	v_mov_b32_e32 v121, v0
	v_mov_b32_e32 v122, v0
	v_mov_b32_e32 v123, v0
	v_mov_b32_e32 v124, v0
	v_mov_b32_e32 v125, v0
	v_mov_b32_e32 v126, v0
	v_mov_b32_e32 v127, v0
	v_mov_b32_e32 v80, v0
	v_mov_b32_e32 v81, v0
	v_mov_b32_e32 v82, v0
	v_mov_b32_e32 v83, v0
	v_mov_b32_e32 v84, v0
	v_mov_b32_e32 v85, v0
	v_mov_b32_e32 v86, v0
	v_mov_b32_e32 v87, v0
	v_mov_b32_e32 v96, v0
	v_mov_b32_e32 v97, v0
	v_mov_b32_e32 v98, v0
	v_mov_b32_e32 v99, v0
	v_mov_b32_e32 v100, v0
	v_mov_b32_e32 v101, v0
	v_mov_b32_e32 v102, v0
	v_mov_b32_e32 v103, v0
	v_mov_b32_e32 v112, v0
	v_mov_b32_e32 v113, v0
	v_mov_b32_e32 v114, v0
	v_mov_b32_e32 v115, v0
	v_mov_b32_e32 v116, v0
	v_mov_b32_e32 v117, v0
	v_mov_b32_e32 v118, v0
	v_mov_b32_e32 v119, v0
	v_mov_b32_e32 v128, v0
	v_mov_b32_e32 v129, v0
	v_mov_b32_e32 v130, v0
	v_mov_b32_e32 v131, v0
	v_mov_b32_e32 v132, v0
	v_mov_b32_e32 v133, v0
	v_mov_b32_e32 v134, v0
	v_mov_b32_e32 v135, v0
	v_readfirstlane_b32 s98, v165
	s_lshr_b32 s98, s98, 8
	s_cmp_eq_u32 s98, 1
	s_cbranch_scc0 .Lprio_skip1
	s_setprio 1
.Lprio_skip1:
.LBB0_854:
	s_add_i32 s79, s24, 2
	s_add_u32 s26, s28, 0x80
	s_addc_u32 s25, s29, 0
	s_add_i32 s82, 0, 0x10000
	s_cmp_eq_u32 s59, s24
	s_cselect_b32 s25, s1, s25
	s_cselect_b32 s24, s0, s26
	v_add_u32_e32 v140, s82, v160
	s_cselect_b32 s81, s47, s31
	s_cselect_b32 s80, s46, s30
	s_add_i32 s26, 0, 0x14000
	ds_read_b128 v[136:139], v140
	ds_read_b128 v[154:157], v140 offset:1024
	ds_read_b128 v[172:175], v140 offset:2048
	ds_read_b128 v[192:195], v140 offset:3072
	v_add_u32_e32 v140, s26, v160
	ds_read_b128 v[196:199], v140
	ds_read_b128 v[200:203], v140 offset:1024
	ds_read_b128 v[204:207], v140 offset:2048
	ds_read_b128 v[208:211], v140 offset:3072
	v_lshl_add_u64 v[140:141], s[28:29], 0, v[150:151]
	s_add_i32 m0, s51, 0xc000
	ds_read_b128 v[212:215], v162
	ds_read_b128 v[216:219], v162 offset:1024
	ds_read_b128 v[220:223], v162 offset:2048
	ds_read_b128 v[224:227], v162 offset:3072
	ds_read_b128 v[228:231], v162 offset:4096
	ds_read_b128 v[232:235], v162 offset:5120
	ds_read_b128 v[236:239], v162 offset:6144
	ds_read_b128 v[240:243], v162 offset:7168
	global_load_lds_dwordx4 v[140:141], off
	v_lshl_add_u64 v[140:141], s[28:29], 0, v[152:153]
	s_add_i32 m0, s51, 0xe000
	s_nop 0
	global_load_lds_dwordx4 v[140:141], off
	s_waitcnt vmcnt(8)
	s_waitcnt lgkmcnt(0)
	s_barrier
	s_waitcnt lgkmcnt(0)
	v_mfma_f32_16x16x32_bf16 v[132:135], v[136:139], v[212:215], v[132:135]
	v_mfma_f32_16x16x32_bf16 v[128:131], v[172:175], v[212:215], v[128:131]
	v_mfma_f32_16x16x32_bf16 v[116:119], v[136:139], v[220:223], v[116:119]
	v_mfma_f32_16x16x32_bf16 v[112:115], v[172:175], v[220:223], v[112:115]
	v_mfma_f32_16x16x32_bf16 v[100:103], v[136:139], v[228:231], v[100:103]
	v_mfma_f32_16x16x32_bf16 v[96:99], v[172:175], v[228:231], v[96:99]
	v_mfma_f32_16x16x32_bf16 v[84:87], v[136:139], v[236:239], v[84:87]
	v_mfma_f32_16x16x32_bf16 v[80:83], v[172:175], v[236:239], v[80:83]
	v_mfma_f32_16x16x32_bf16 v[132:135], v[154:157], v[216:219], v[132:135]
	v_mfma_f32_16x16x32_bf16 v[128:131], v[192:195], v[216:219], v[128:131]
	v_mfma_f32_16x16x32_bf16 v[116:119], v[154:157], v[224:227], v[116:119]
	v_mfma_f32_16x16x32_bf16 v[112:115], v[192:195], v[224:227], v[112:115]
	v_mfma_f32_16x16x32_bf16 v[100:103], v[154:157], v[232:235], v[100:103]
	v_mfma_f32_16x16x32_bf16 v[96:99], v[192:195], v[232:235], v[96:99]
	v_mfma_f32_16x16x32_bf16 v[84:87], v[154:157], v[240:243], v[84:87]
	v_mfma_f32_16x16x32_bf16 v[80:83], v[192:195], v[240:243], v[80:83]
	v_mfma_f32_16x16x32_bf16 v[124:127], v[196:199], v[212:215], v[124:127]
	v_mfma_f32_16x16x32_bf16 v[120:123], v[204:207], v[212:215], v[120:123]
	v_mfma_f32_16x16x32_bf16 v[108:111], v[196:199], v[220:223], v[108:111]
	v_mfma_f32_16x16x32_bf16 v[104:107], v[204:207], v[220:223], v[104:107]
	v_mfma_f32_16x16x32_bf16 v[92:95], v[196:199], v[228:231], v[92:95]
	v_mfma_f32_16x16x32_bf16 v[88:91], v[204:207], v[228:231], v[88:91]
	v_mfma_f32_16x16x32_bf16 v[76:79], v[196:199], v[236:239], v[76:79]
	v_mfma_f32_16x16x32_bf16 v[72:75], v[204:207], v[236:239], v[72:75]
	v_mfma_f32_16x16x32_bf16 v[124:127], v[200:203], v[216:219], v[124:127]
	v_mfma_f32_16x16x32_bf16 v[120:123], v[208:211], v[216:219], v[120:123]
	v_mfma_f32_16x16x32_bf16 v[108:111], v[200:203], v[224:227], v[108:111]
	v_mfma_f32_16x16x32_bf16 v[104:107], v[208:211], v[224:227], v[104:107]
	v_mfma_f32_16x16x32_bf16 v[92:95], v[200:203], v[232:235], v[92:95]
	v_mfma_f32_16x16x32_bf16 v[88:91], v[208:211], v[232:235], v[88:91]
	v_mfma_f32_16x16x32_bf16 v[76:79], v[200:203], v[240:243], v[76:79]
	v_mfma_f32_16x16x32_bf16 v[72:75], v[208:211], v[240:243], v[72:75]
	s_barrier
	s_add_i32 s82, s82, s50
	v_lshl_add_u64 v[140:141], s[80:81], 0, v[144:145]
	s_mov_b32 m0, s82
	ds_read_b128 v[212:215], v162 offset:16384
	ds_read_b128 v[216:219], v162 offset:17408
	ds_read_b128 v[220:223], v162 offset:18432
	ds_read_b128 v[224:227], v162 offset:19456
	ds_read_b128 v[228:231], v162 offset:20480
	ds_read_b128 v[232:235], v162 offset:21504
	ds_read_b128 v[236:239], v162 offset:22528
	ds_read_b128 v[240:243], v162 offset:23552
	global_load_lds_dwordx4 v[140:141], off
	s_add_i32 m0, s82, 0x2000
	v_lshl_add_u64 v[142:143], s[80:81], 0, v[148:149]
	s_add_u32 s80, s80, s2
	s_addc_u32 s81, s81, 0
	s_add_i32 s26, s26, s50
	global_load_lds_dwordx4 v[142:143], off
	v_lshl_add_u64 v[158:159], s[80:81], 0, v[144:145]
	s_mov_b32 m0, s26
	v_lshl_add_u64 v[168:169], s[80:81], 0, v[148:149]
	global_load_lds_dwordx4 v[158:159], off
	s_add_i32 m0, s26, 0x2000
	v_lshl_add_u64 v[176:177], s[24:25], 0, v[34:35]
	global_load_lds_dwordx4 v[168:169], off
	s_mov_b32 m0, s51
	v_lshl_add_u64 v[244:245], s[24:25], 0, v[146:147]
	global_load_lds_dwordx4 v[176:177], off
	s_mov_b32 m0, s52
	s_nop 0
	global_load_lds_dwordx4 v[244:245], off
	s_waitcnt vmcnt(8)
	s_waitcnt lgkmcnt(0)
	s_barrier
	s_waitcnt lgkmcnt(0)
	v_mfma_f32_16x16x32_bf16 v[68:71], v[136:139], v[212:215], v[68:71]
	v_mfma_f32_16x16x32_bf16 v[64:67], v[172:175], v[212:215], v[64:67]
	v_mfma_f32_16x16x32_bf16 v[52:55], v[136:139], v[220:223], v[52:55]
	v_mfma_f32_16x16x32_bf16 v[48:51], v[172:175], v[220:223], v[48:51]
	v_mfma_f32_16x16x32_bf16 v[28:31], v[136:139], v[228:231], v[28:31]
	v_mfma_f32_16x16x32_bf16 v[24:27], v[172:175], v[228:231], v[24:27]
	v_mfma_f32_16x16x32_bf16 v[12:15], v[136:139], v[236:239], v[12:15]
	v_mfma_f32_16x16x32_bf16 v[8:11], v[172:175], v[236:239], v[8:11]
	v_mfma_f32_16x16x32_bf16 v[68:71], v[154:157], v[216:219], v[68:71]
	v_mfma_f32_16x16x32_bf16 v[64:67], v[192:195], v[216:219], v[64:67]
	v_mfma_f32_16x16x32_bf16 v[52:55], v[154:157], v[224:227], v[52:55]
	v_mfma_f32_16x16x32_bf16 v[48:51], v[192:195], v[224:227], v[48:51]
	v_mfma_f32_16x16x32_bf16 v[28:31], v[154:157], v[232:235], v[28:31]
	v_mfma_f32_16x16x32_bf16 v[24:27], v[192:195], v[232:235], v[24:27]
	v_mfma_f32_16x16x32_bf16 v[12:15], v[154:157], v[240:243], v[12:15]
	v_mfma_f32_16x16x32_bf16 v[8:11], v[192:195], v[240:243], v[8:11]
	v_mfma_f32_16x16x32_bf16 v[60:63], v[196:199], v[212:215], v[60:63]
	v_mfma_f32_16x16x32_bf16 v[56:59], v[204:207], v[212:215], v[56:59]
	v_mfma_f32_16x16x32_bf16 v[44:47], v[196:199], v[220:223], v[44:47]
	v_mfma_f32_16x16x32_bf16 v[40:43], v[204:207], v[220:223], v[40:43]
	v_mfma_f32_16x16x32_bf16 v[20:23], v[196:199], v[228:231], v[20:23]
	v_mfma_f32_16x16x32_bf16 v[16:19], v[204:207], v[228:231], v[16:19]
	v_mfma_f32_16x16x32_bf16 v[4:7], v[196:199], v[236:239], v[4:7]
	v_mfma_f32_16x16x32_bf16 v[0:3], v[204:207], v[236:239], v[0:3]
	v_mfma_f32_16x16x32_bf16 v[60:63], v[200:203], v[216:219], v[60:63]
	v_mfma_f32_16x16x32_bf16 v[56:59], v[208:211], v[216:219], v[56:59]
	v_mfma_f32_16x16x32_bf16 v[44:47], v[200:203], v[224:227], v[44:47]
	v_mfma_f32_16x16x32_bf16 v[40:43], v[208:211], v[224:227], v[40:43]
	v_mfma_f32_16x16x32_bf16 v[20:23], v[200:203], v[232:235], v[20:23]
	v_mfma_f32_16x16x32_bf16 v[16:19], v[208:211], v[232:235], v[16:19]
	v_mfma_f32_16x16x32_bf16 v[4:7], v[200:203], v[240:243], v[4:7]
	v_mfma_f32_16x16x32_bf16 v[0:3], v[208:211], v[240:243], v[0:3]
	s_barrier
	s_add_i32 s26, 0, 0x18000
	v_add_u32_e32 v163, s26, v160
	s_add_i32 s80, 0, 0x1c000
	ds_read_b128 v[136:139], v163
	ds_read_b128 v[154:157], v163 offset:1024
	ds_read_b128 v[172:175], v163 offset:2048
	ds_read_b128 v[192:195], v163 offset:3072
	v_add_u32_e32 v163, s80, v160
	ds_read_b128 v[196:199], v163
	ds_read_b128 v[200:203], v163 offset:1024
	ds_read_b128 v[204:207], v163 offset:2048
	ds_read_b128 v[208:211], v163 offset:3072
	s_add_u32 s24, s24, s2
	s_addc_u32 s25, s25, 0
	s_mov_b32 m0, s53
	v_lshl_add_u64 v[246:247], s[24:25], 0, v[34:35]
	ds_read_b128 v[212:215], v162 offset:32768
	ds_read_b128 v[216:219], v162 offset:33792
	ds_read_b128 v[220:223], v162 offset:34816
	ds_read_b128 v[224:227], v162 offset:35840
	ds_read_b128 v[228:231], v162 offset:36864
	ds_read_b128 v[232:235], v162 offset:37888
	ds_read_b128 v[236:239], v162 offset:38912
	ds_read_b128 v[240:243], v162 offset:39936
	global_load_lds_dwordx4 v[246:247], off
	v_lshl_add_u64 v[246:247], s[24:25], 0, v[146:147]
	s_mov_b32 m0, s54
	s_nop 0
	global_load_lds_dwordx4 v[246:247], off
	s_waitcnt vmcnt(8)
	s_waitcnt lgkmcnt(0)
	s_barrier
	s_waitcnt lgkmcnt(0)
	v_mfma_f32_16x16x32_bf16 v[132:135], v[136:139], v[212:215], v[132:135]
	v_mfma_f32_16x16x32_bf16 v[128:131], v[172:175], v[212:215], v[128:131]
	v_mfma_f32_16x16x32_bf16 v[116:119], v[136:139], v[220:223], v[116:119]
	v_mfma_f32_16x16x32_bf16 v[112:115], v[172:175], v[220:223], v[112:115]
	v_mfma_f32_16x16x32_bf16 v[100:103], v[136:139], v[228:231], v[100:103]
	v_mfma_f32_16x16x32_bf16 v[96:99], v[172:175], v[228:231], v[96:99]
	v_mfma_f32_16x16x32_bf16 v[84:87], v[136:139], v[236:239], v[84:87]
	v_mfma_f32_16x16x32_bf16 v[80:83], v[172:175], v[236:239], v[80:83]
	v_mfma_f32_16x16x32_bf16 v[132:135], v[154:157], v[216:219], v[132:135]
	v_mfma_f32_16x16x32_bf16 v[128:131], v[192:195], v[216:219], v[128:131]
	v_mfma_f32_16x16x32_bf16 v[116:119], v[154:157], v[224:227], v[116:119]
	v_mfma_f32_16x16x32_bf16 v[112:115], v[192:195], v[224:227], v[112:115]
	v_mfma_f32_16x16x32_bf16 v[100:103], v[154:157], v[232:235], v[100:103]
	v_mfma_f32_16x16x32_bf16 v[96:99], v[192:195], v[232:235], v[96:99]
	v_mfma_f32_16x16x32_bf16 v[84:87], v[154:157], v[240:243], v[84:87]
	v_mfma_f32_16x16x32_bf16 v[80:83], v[192:195], v[240:243], v[80:83]
	v_mfma_f32_16x16x32_bf16 v[124:127], v[196:199], v[212:215], v[124:127]
	v_mfma_f32_16x16x32_bf16 v[120:123], v[204:207], v[212:215], v[120:123]
	v_mfma_f32_16x16x32_bf16 v[108:111], v[196:199], v[220:223], v[108:111]
	v_mfma_f32_16x16x32_bf16 v[104:107], v[204:207], v[220:223], v[104:107]
	v_mfma_f32_16x16x32_bf16 v[92:95], v[196:199], v[228:231], v[92:95]
	v_mfma_f32_16x16x32_bf16 v[88:91], v[204:207], v[228:231], v[88:91]
	v_mfma_f32_16x16x32_bf16 v[76:79], v[196:199], v[236:239], v[76:79]
	v_mfma_f32_16x16x32_bf16 v[72:75], v[204:207], v[236:239], v[72:75]
	v_mfma_f32_16x16x32_bf16 v[124:127], v[200:203], v[216:219], v[124:127]
	v_mfma_f32_16x16x32_bf16 v[120:123], v[208:211], v[216:219], v[120:123]
	v_mfma_f32_16x16x32_bf16 v[108:111], v[200:203], v[224:227], v[108:111]
	v_mfma_f32_16x16x32_bf16 v[104:107], v[208:211], v[224:227], v[104:107]
	v_mfma_f32_16x16x32_bf16 v[92:95], v[200:203], v[232:235], v[92:95]
	v_mfma_f32_16x16x32_bf16 v[88:91], v[208:211], v[232:235], v[88:91]
	v_mfma_f32_16x16x32_bf16 v[76:79], v[200:203], v[240:243], v[76:79]
	v_mfma_f32_16x16x32_bf16 v[72:75], v[208:211], v[240:243], v[72:75]
	s_barrier
	s_add_i32 s24, s26, s50
	v_lshl_add_u64 v[140:141], v[140:141], 0, s[60:61]
	s_mov_b32 m0, s24
	ds_read_b128 v[212:215], v162 offset:49152
	ds_read_b128 v[216:219], v162 offset:50176
	ds_read_b128 v[220:223], v162 offset:51200
	ds_read_b128 v[224:227], v162 offset:52224
	ds_read_b128 v[228:231], v162 offset:53248
	ds_read_b128 v[232:235], v162 offset:54272
	ds_read_b128 v[236:239], v162 offset:55296
	ds_read_b128 v[240:243], v162 offset:56320
	global_load_lds_dwordx4 v[140:141], off
	v_lshl_add_u64 v[140:141], v[142:143], 0, s[60:61]
	s_add_i32 m0, s24, 0x2000
	s_add_i32 s24, s80, s50
	global_load_lds_dwordx4 v[140:141], off
	v_lshl_add_u64 v[140:141], v[158:159], 0, s[60:61]
	s_mov_b32 m0, s24
	s_nop 0
	global_load_lds_dwordx4 v[140:141], off
	v_lshl_add_u64 v[140:141], v[168:169], 0, s[60:61]
	s_add_i32 m0, s24, 0x2000
	s_nop 0
	global_load_lds_dwordx4 v[140:141], off
	v_lshl_add_u64 v[140:141], v[176:177], 0, s[60:61]
	s_mov_b32 m0, s57
	s_nop 0
	global_load_lds_dwordx4 v[140:141], off
	v_lshl_add_u64 v[140:141], v[244:245], 0, s[60:61]
	s_mov_b32 m0, s58
	s_nop 0
	global_load_lds_dwordx4 v[140:141], off
	s_waitcnt vmcnt(8)
	s_waitcnt lgkmcnt(0)
	s_barrier
	s_waitcnt lgkmcnt(0)
	v_mfma_f32_16x16x32_bf16 v[68:71], v[136:139], v[212:215], v[68:71]
	v_mfma_f32_16x16x32_bf16 v[64:67], v[172:175], v[212:215], v[64:67]
	v_mfma_f32_16x16x32_bf16 v[52:55], v[136:139], v[220:223], v[52:55]
	v_mfma_f32_16x16x32_bf16 v[48:51], v[172:175], v[220:223], v[48:51]
	v_mfma_f32_16x16x32_bf16 v[28:31], v[136:139], v[228:231], v[28:31]
	v_mfma_f32_16x16x32_bf16 v[24:27], v[172:175], v[228:231], v[24:27]
	v_mfma_f32_16x16x32_bf16 v[12:15], v[136:139], v[236:239], v[12:15]
	v_mfma_f32_16x16x32_bf16 v[8:11], v[172:175], v[236:239], v[8:11]
	v_mfma_f32_16x16x32_bf16 v[68:71], v[154:157], v[216:219], v[68:71]
	v_mfma_f32_16x16x32_bf16 v[64:67], v[192:195], v[216:219], v[64:67]
	v_mfma_f32_16x16x32_bf16 v[52:55], v[154:157], v[224:227], v[52:55]
	v_mfma_f32_16x16x32_bf16 v[48:51], v[192:195], v[224:227], v[48:51]
	v_mfma_f32_16x16x32_bf16 v[28:31], v[154:157], v[232:235], v[28:31]
	v_mfma_f32_16x16x32_bf16 v[24:27], v[192:195], v[232:235], v[24:27]
	v_mfma_f32_16x16x32_bf16 v[12:15], v[154:157], v[240:243], v[12:15]
	v_mfma_f32_16x16x32_bf16 v[8:11], v[192:195], v[240:243], v[8:11]
	v_mfma_f32_16x16x32_bf16 v[60:63], v[196:199], v[212:215], v[60:63]
	v_mfma_f32_16x16x32_bf16 v[56:59], v[204:207], v[212:215], v[56:59]
	v_mfma_f32_16x16x32_bf16 v[44:47], v[196:199], v[220:223], v[44:47]
	v_mfma_f32_16x16x32_bf16 v[40:43], v[204:207], v[220:223], v[40:43]
	v_mfma_f32_16x16x32_bf16 v[20:23], v[196:199], v[228:231], v[20:23]
	v_mfma_f32_16x16x32_bf16 v[16:19], v[204:207], v[228:231], v[16:19]
	v_mfma_f32_16x16x32_bf16 v[4:7], v[196:199], v[236:239], v[4:7]
	v_mfma_f32_16x16x32_bf16 v[0:3], v[204:207], v[236:239], v[0:3]
	v_mfma_f32_16x16x32_bf16 v[60:63], v[200:203], v[216:219], v[60:63]
	v_mfma_f32_16x16x32_bf16 v[56:59], v[208:211], v[216:219], v[56:59]
	v_mfma_f32_16x16x32_bf16 v[44:47], v[200:203], v[224:227], v[44:47]
	v_mfma_f32_16x16x32_bf16 v[40:43], v[208:211], v[224:227], v[40:43]
	v_mfma_f32_16x16x32_bf16 v[20:23], v[200:203], v[232:235], v[20:23]
	v_mfma_f32_16x16x32_bf16 v[16:19], v[208:211], v[232:235], v[16:19]
	v_mfma_f32_16x16x32_bf16 v[4:7], v[200:203], v[240:243], v[4:7]
	v_mfma_f32_16x16x32_bf16 v[0:3], v[208:211], v[240:243], v[0:3]
	s_barrier
	s_add_u32 s28, s28, 0x100
	s_addc_u32 s29, s29, 0
	s_add_u32 s30, s30, 0x100
	s_addc_u32 s31, s31, 0
	s_cmp_ge_u32 s79, s56
	s_mov_b32 s24, s79
	s_cbranch_scc0 .LBB0_854
	s_setprio 0
	s_and_b64 vcc, exec, s[44:45]
	s_cbranch_vccz .LBB0_857
	s_barrier

.LBB0_898:
	s_add_u32 s0, s70, 0x80
	s_addc_u32 s1, s71, 0
	s_add_u32 s70, s24, 0x100
	v_mov_b32_e32 v0, 0
	s_addc_u32 s71, s25, 0
	s_mov_b32 s24, 0
	v_mov_b32_e32 v1, v0
	v_mov_b32_e32 v2, v0
	v_mov_b32_e32 v3, v0
	v_mov_b32_e32 v4, v0
	v_mov_b32_e32 v5, v0
	v_mov_b32_e32 v6, v0
	v_mov_b32_e32 v7, v0
	v_mov_b32_e32 v8, v0
	v_mov_b32_e32 v9, v0
	v_mov_b32_e32 v10, v0
	v_mov_b32_e32 v11, v0
	v_mov_b32_e32 v16, v0
	v_mov_b32_e32 v17, v0
	v_mov_b32_e32 v18, v0
	v_mov_b32_e32 v19, v0
	v_mov_b32_e32 v24, v0
	v_mov_b32_e32 v25, v0
	v_mov_b32_e32 v26, v0
	v_mov_b32_e32 v27, v0
	v_mov_b32_e32 v40, v0
	v_mov_b32_e32 v41, v0
	v_mov_b32_e32 v42, v0
	v_mov_b32_e32 v43, v0
	v_mov_b32_e32 v48, v0
	v_mov_b32_e32 v49, v0
	v_mov_b32_e32 v50, v0
	v_mov_b32_e32 v51, v0
	v_mov_b32_e32 v56, v0
	v_mov_b32_e32 v57, v0
	v_mov_b32_e32 v58, v0
	v_mov_b32_e32 v59, v0
	v_mov_b32_e32 v12, v0
	v_mov_b32_e32 v13, v0
	v_mov_b32_e32 v14, v0
	v_mov_b32_e32 v15, v0
	v_mov_b32_e32 v20, v0
	v_mov_b32_e32 v21, v0
	v_mov_b32_e32 v22, v0
	v_mov_b32_e32 v23, v0
	v_mov_b32_e32 v28, v0
	v_mov_b32_e32 v29, v0
	v_mov_b32_e32 v30, v0
	v_mov_b32_e32 v31, v0
	v_mov_b32_e32 v44, v0
	v_mov_b32_e32 v45, v0
	v_mov_b32_e32 v46, v0
	v_mov_b32_e32 v47, v0
	v_mov_b32_e32 v52, v0
	v_mov_b32_e32 v53, v0
	v_mov_b32_e32 v54, v0
	v_mov_b32_e32 v55, v0
	v_mov_b32_e32 v60, v0
	v_mov_b32_e32 v61, v0
	v_mov_b32_e32 v62, v0
	v_mov_b32_e32 v63, v0
	v_mov_b32_e32 v64, v0
	v_mov_b32_e32 v65, v0
	v_mov_b32_e32 v66, v0
	v_mov_b32_e32 v67, v0
	v_mov_b32_e32 v68, v0
	v_mov_b32_e32 v69, v0
	v_mov_b32_e32 v70, v0
	v_mov_b32_e32 v71, v0
	v_mov_b32_e32 v72, v0
	v_mov_b32_e32 v73, v0
	v_mov_b32_e32 v74, v0
	v_mov_b32_e32 v75, v0
	v_mov_b32_e32 v76, v0
	v_mov_b32_e32 v77, v0
	v_mov_b32_e32 v78, v0
	v_mov_b32_e32 v79, v0
	v_mov_b32_e32 v80, v0
	v_mov_b32_e32 v81, v0
	v_mov_b32_e32 v82, v0
	v_mov_b32_e32 v83, v0
	s_waitcnt vmcnt(0)
	v_mov_b32_e32 v88, v0
	v_mov_b32_e32 v89, v0
	v_mov_b32_e32 v90, v0
	v_mov_b32_e32 v91, v0
	v_mov_b32_e32 v96, v0
	v_mov_b32_e32 v97, v0
	v_mov_b32_e32 v98, v0
	v_mov_b32_e32 v99, v0
	v_mov_b32_e32 v104, v0
	v_mov_b32_e32 v105, v0
	v_mov_b32_e32 v106, v0
	v_mov_b32_e32 v107, v0
	v_mov_b32_e32 v112, v0
	v_mov_b32_e32 v113, v0
	v_mov_b32_e32 v114, v0
	v_mov_b32_e32 v115, v0
	v_mov_b32_e32 v120, v0
	v_mov_b32_e32 v121, v0
	v_mov_b32_e32 v122, v0
	v_mov_b32_e32 v123, v0
	v_mov_b32_e32 v84, v0
	v_mov_b32_e32 v85, v0
	v_mov_b32_e32 v86, v0
	v_mov_b32_e32 v87, v0
	v_mov_b32_e32 v92, v0
	v_mov_b32_e32 v93, v0
	v_mov_b32_e32 v94, v0
	v_mov_b32_e32 v95, v0
	v_mov_b32_e32 v100, v0
	v_mov_b32_e32 v101, v0
	v_mov_b32_e32 v102, v0
	v_mov_b32_e32 v103, v0
	v_mov_b32_e32 v108, v0
	v_mov_b32_e32 v109, v0
	v_mov_b32_e32 v110, v0
	v_mov_b32_e32 v111, v0
	v_mov_b32_e32 v116, v0
	v_mov_b32_e32 v117, v0
	v_mov_b32_e32 v118, v0
	v_mov_b32_e32 v119, v0
	v_mov_b32_e32 v124, v0
	v_mov_b32_e32 v125, v0
	v_mov_b32_e32 v126, v0
	v_mov_b32_e32 v127, v0
	v_mov_b32_e32 v128, v0
	v_mov_b32_e32 v129, v0
	v_mov_b32_e32 v130, v0
	v_mov_b32_e32 v131, v0
	v_mov_b32_e32 v132, v0
	v_mov_b32_e32 v133, v0
	v_mov_b32_e32 v134, v0
	v_mov_b32_e32 v135, v0
	v_readfirstlane_b32 s98, v165
	s_lshr_b32 s98, s98, 8
	s_cmp_eq_u32 s98, 1
	s_cbranch_scc0 .Lprio_skip2
	s_setprio 1
.Lprio_skip2:
.LBB0_899:
	s_add_i32 vcc_lo, s24, 2
	s_add_u32 s28, s0, 0x80
	s_addc_u32 s25, s1, 0
	s_add_i32 vcc_hi, 0, 0x10000
	s_cmp_eq_u32 s85, s24
	s_cselect_b32 s25, s51, s25
	s_cselect_b32 s24, s50, s28
	v_add_u32_e32 v136, vcc_hi, v157
	s_cselect_b32 s29, s69, s71
	s_cselect_b32 s28, s68, s70
	s_add_i32 s26, 0, 0x14000
	ds_read_b128 v[192:195], v136
	ds_read_b128 v[196:199], v136 offset:1024
	ds_read_b128 v[200:203], v136 offset:2048
	ds_read_b128 v[204:207], v136 offset:3072
	v_add_u32_e32 v136, s26, v157
	ds_read_b128 v[208:211], v136
	ds_read_b128 v[212:215], v136 offset:1024
	ds_read_b128 v[216:219], v136 offset:2048
	ds_read_b128 v[220:223], v136 offset:3072
	v_lshl_add_u64 v[154:155], s[0:1], 0, v[150:151]
	s_add_i32 m0, s82, 0xc000
	ds_read_b128 v[224:227], v161
	ds_read_b128 v[228:231], v161 offset:1024
	ds_read_b128 v[232:235], v161 offset:2048
	ds_read_b128 v[236:239], v161 offset:3072
	ds_read_b128 v[240:243], v161 offset:4096
	ds_read_b128 v[244:247], v161 offset:5120
	ds_read_b128 v[136:139], v161 offset:6144
	ds_read_b128 v[172:175], v161 offset:7168
	global_load_lds_dwordx4 v[154:155], off
	v_lshl_add_u64 v[154:155], s[0:1], 0, v[152:153]
	s_add_i32 m0, s82, 0xe000
	s_nop 0
	global_load_lds_dwordx4 v[154:155], off
	s_waitcnt vmcnt(8)
	s_waitcnt lgkmcnt(0)
	s_barrier
	s_waitcnt lgkmcnt(0)
	v_mfma_f32_16x16x32_bf16 v[132:135], v[192:195], v[224:227], v[132:135]
	v_mfma_f32_16x16x32_bf16 v[128:131], v[200:203], v[224:227], v[128:131]
	v_mfma_f32_16x16x32_bf16 v[124:127], v[192:195], v[232:235], v[124:127]
	v_mfma_f32_16x16x32_bf16 v[116:119], v[200:203], v[232:235], v[116:119]
	v_mfma_f32_16x16x32_bf16 v[108:111], v[192:195], v[240:243], v[108:111]
	v_mfma_f32_16x16x32_bf16 v[100:103], v[200:203], v[240:243], v[100:103]
	v_mfma_f32_16x16x32_bf16 v[92:95], v[192:195], v[136:139], v[92:95]
	v_mfma_f32_16x16x32_bf16 v[84:87], v[200:203], v[136:139], v[84:87]
	v_mfma_f32_16x16x32_bf16 v[132:135], v[196:199], v[228:231], v[132:135]
	v_mfma_f32_16x16x32_bf16 v[128:131], v[204:207], v[228:231], v[128:131]
	v_mfma_f32_16x16x32_bf16 v[124:127], v[196:199], v[236:239], v[124:127]
	v_mfma_f32_16x16x32_bf16 v[116:119], v[204:207], v[236:239], v[116:119]
	v_mfma_f32_16x16x32_bf16 v[108:111], v[196:199], v[244:247], v[108:111]
	v_mfma_f32_16x16x32_bf16 v[100:103], v[204:207], v[244:247], v[100:103]
	v_mfma_f32_16x16x32_bf16 v[92:95], v[196:199], v[172:175], v[92:95]
	v_mfma_f32_16x16x32_bf16 v[84:87], v[204:207], v[172:175], v[84:87]
	v_mfma_f32_16x16x32_bf16 v[120:123], v[208:211], v[224:227], v[120:123]
	v_mfma_f32_16x16x32_bf16 v[112:115], v[216:219], v[224:227], v[112:115]
	v_mfma_f32_16x16x32_bf16 v[104:107], v[208:211], v[232:235], v[104:107]
	v_mfma_f32_16x16x32_bf16 v[96:99], v[216:219], v[232:235], v[96:99]
	v_mfma_f32_16x16x32_bf16 v[88:91], v[208:211], v[240:243], v[88:91]
	v_mfma_f32_16x16x32_bf16 v[80:83], v[216:219], v[240:243], v[80:83]
	v_mfma_f32_16x16x32_bf16 v[76:79], v[208:211], v[136:139], v[76:79]
	v_mfma_f32_16x16x32_bf16 v[72:75], v[216:219], v[136:139], v[72:75]
	v_mfma_f32_16x16x32_bf16 v[120:123], v[212:215], v[228:231], v[120:123]
	v_mfma_f32_16x16x32_bf16 v[112:115], v[220:223], v[228:231], v[112:115]
	v_mfma_f32_16x16x32_bf16 v[104:107], v[212:215], v[236:239], v[104:107]
	v_mfma_f32_16x16x32_bf16 v[96:99], v[220:223], v[236:239], v[96:99]
	v_mfma_f32_16x16x32_bf16 v[88:91], v[212:215], v[244:247], v[88:91]
	v_mfma_f32_16x16x32_bf16 v[80:83], v[220:223], v[244:247], v[80:83]
	v_mfma_f32_16x16x32_bf16 v[76:79], v[212:215], v[172:175], v[76:79]
	v_mfma_f32_16x16x32_bf16 v[72:75], v[220:223], v[172:175], v[72:75]
	s_barrier
	s_add_i32 vcc_hi, vcc_hi, s81
	v_lshl_add_u64 v[154:155], s[28:29], 0, v[144:145]
	s_mov_b32 m0, vcc_hi
	ds_read_b128 v[136:139], v161 offset:16384
	ds_read_b128 v[172:175], v161 offset:17408
	ds_read_b128 v[224:227], v161 offset:18432
	ds_read_b128 v[228:231], v161 offset:19456
	ds_read_b128 v[232:235], v161 offset:20480
	ds_read_b128 v[236:239], v161 offset:21504
	ds_read_b128 v[240:243], v161 offset:22528
	ds_read_b128 v[244:247], v161 offset:23552
	global_load_lds_dwordx4 v[154:155], off
	s_add_i32 m0, vcc_hi, 0x2000
	v_lshl_add_u64 v[162:163], s[28:29], 0, v[148:149]
	s_add_u32 s28, s28, s39
	s_addc_u32 s29, s29, 0
	s_add_i32 s26, s26, s81
	global_load_lds_dwordx4 v[162:163], off
	v_lshl_add_u64 v[168:169], s[28:29], 0, v[144:145]
	s_mov_b32 m0, s26
	v_lshl_add_u64 v[176:177], s[28:29], 0, v[148:149]
	global_load_lds_dwordx4 v[168:169], off
	s_add_i32 m0, s26, 0x2000
	v_lshl_add_u64 v[248:249], s[24:25], 0, v[34:35]
	global_load_lds_dwordx4 v[176:177], off
	s_mov_b32 m0, s82
	v_lshl_add_u64 v[140:141], s[24:25], 0, v[146:147]
	global_load_lds_dwordx4 v[248:249], off
	s_mov_b32 m0, s83
	s_nop 0
	global_load_lds_dwordx4 v[140:141], off
	s_waitcnt vmcnt(8)
	s_waitcnt lgkmcnt(0)
	s_barrier
	s_waitcnt lgkmcnt(0)
	v_mfma_f32_16x16x32_bf16 v[68:71], v[192:195], v[136:139], v[68:71]
	v_mfma_f32_16x16x32_bf16 v[64:67], v[200:203], v[136:139], v[64:67]
	v_mfma_f32_16x16x32_bf16 v[60:63], v[192:195], v[224:227], v[60:63]
	v_mfma_f32_16x16x32_bf16 v[52:55], v[200:203], v[224:227], v[52:55]
	v_mfma_f32_16x16x32_bf16 v[44:47], v[192:195], v[232:235], v[44:47]
	v_mfma_f32_16x16x32_bf16 v[28:31], v[200:203], v[232:235], v[28:31]
	v_mfma_f32_16x16x32_bf16 v[20:23], v[192:195], v[240:243], v[20:23]
	v_mfma_f32_16x16x32_bf16 v[12:15], v[200:203], v[240:243], v[12:15]
	v_mfma_f32_16x16x32_bf16 v[68:71], v[196:199], v[172:175], v[68:71]
	v_mfma_f32_16x16x32_bf16 v[64:67], v[204:207], v[172:175], v[64:67]
	v_mfma_f32_16x16x32_bf16 v[60:63], v[196:199], v[228:231], v[60:63]
	v_mfma_f32_16x16x32_bf16 v[52:55], v[204:207], v[228:231], v[52:55]
	v_mfma_f32_16x16x32_bf16 v[44:47], v[196:199], v[236:239], v[44:47]
	v_mfma_f32_16x16x32_bf16 v[28:31], v[204:207], v[236:239], v[28:31]
	v_mfma_f32_16x16x32_bf16 v[20:23], v[196:199], v[244:247], v[20:23]
	v_mfma_f32_16x16x32_bf16 v[12:15], v[204:207], v[244:247], v[12:15]
	v_mfma_f32_16x16x32_bf16 v[56:59], v[208:211], v[136:139], v[56:59]
	v_mfma_f32_16x16x32_bf16 v[48:51], v[216:219], v[136:139], v[48:51]
	v_mfma_f32_16x16x32_bf16 v[40:43], v[208:211], v[224:227], v[40:43]
	v_mfma_f32_16x16x32_bf16 v[24:27], v[216:219], v[224:227], v[24:27]
	v_mfma_f32_16x16x32_bf16 v[16:19], v[208:211], v[232:235], v[16:19]
	v_mfma_f32_16x16x32_bf16 v[8:11], v[216:219], v[232:235], v[8:11]
	v_mfma_f32_16x16x32_bf16 v[4:7], v[208:211], v[240:243], v[4:7]
	v_mfma_f32_16x16x32_bf16 v[0:3], v[216:219], v[240:243], v[0:3]
	v_mfma_f32_16x16x32_bf16 v[56:59], v[212:215], v[172:175], v[56:59]
	v_mfma_f32_16x16x32_bf16 v[48:51], v[220:223], v[172:175], v[48:51]
	v_mfma_f32_16x16x32_bf16 v[40:43], v[212:215], v[228:231], v[40:43]
	v_mfma_f32_16x16x32_bf16 v[24:27], v[220:223], v[228:231], v[24:27]
	v_mfma_f32_16x16x32_bf16 v[16:19], v[212:215], v[236:239], v[16:19]
	v_mfma_f32_16x16x32_bf16 v[8:11], v[220:223], v[236:239], v[8:11]
	v_mfma_f32_16x16x32_bf16 v[4:7], v[212:215], v[244:247], v[4:7]
	v_mfma_f32_16x16x32_bf16 v[0:3], v[220:223], v[244:247], v[0:3]
	s_barrier
	s_add_i32 s26, 0, 0x18000
	v_add_u32_e32 v142, s26, v157
	s_add_i32 s28, 0, 0x1c000
	ds_read_b128 v[136:139], v142
	ds_read_b128 v[172:175], v142 offset:1024
	ds_read_b128 v[192:195], v142 offset:2048
	ds_read_b128 v[196:199], v142 offset:3072
	v_add_u32_e32 v142, s28, v157
	ds_read_b128 v[200:203], v142
	ds_read_b128 v[204:207], v142 offset:1024
	ds_read_b128 v[208:211], v142 offset:2048
	ds_read_b128 v[212:215], v142 offset:3072
	s_add_u32 s24, s24, s76
	s_addc_u32 s25, s25, 0
	s_mov_b32 m0, s86
	v_lshl_add_u64 v[142:143], s[24:25], 0, v[34:35]
	ds_read_b128 v[216:219], v161 offset:32768
	ds_read_b128 v[220:223], v161 offset:33792
	ds_read_b128 v[224:227], v161 offset:34816
	ds_read_b128 v[228:231], v161 offset:35840
	ds_read_b128 v[232:235], v161 offset:36864
	ds_read_b128 v[236:239], v161 offset:37888
	ds_read_b128 v[240:243], v161 offset:38912
	ds_read_b128 v[244:247], v161 offset:39936
	global_load_lds_dwordx4 v[142:143], off
	v_lshl_add_u64 v[142:143], s[24:25], 0, v[146:147]
	s_mov_b32 m0, s88
	s_nop 0
	global_load_lds_dwordx4 v[142:143], off
	s_waitcnt vmcnt(8)
	s_waitcnt lgkmcnt(0)
	s_barrier
	s_waitcnt lgkmcnt(0)
	v_mfma_f32_16x16x32_bf16 v[132:135], v[136:139], v[216:219], v[132:135]
	v_mfma_f32_16x16x32_bf16 v[128:131], v[192:195], v[216:219], v[128:131]
	v_mfma_f32_16x16x32_bf16 v[124:127], v[136:139], v[224:227], v[124:127]
	v_mfma_f32_16x16x32_bf16 v[116:119], v[192:195], v[224:227], v[116:119]
	v_mfma_f32_16x16x32_bf16 v[108:111], v[136:139], v[232:235], v[108:111]
	v_mfma_f32_16x16x32_bf16 v[100:103], v[192:195], v[232:235], v[100:103]
	v_mfma_f32_16x16x32_bf16 v[92:95], v[136:139], v[240:243], v[92:95]
	v_mfma_f32_16x16x32_bf16 v[84:87], v[192:195], v[240:243], v[84:87]
	v_mfma_f32_16x16x32_bf16 v[132:135], v[172:175], v[220:223], v[132:135]
	v_mfma_f32_16x16x32_bf16 v[128:131], v[196:199], v[220:223], v[128:131]
	v_mfma_f32_16x16x32_bf16 v[124:127], v[172:175], v[228:231], v[124:127]
	v_mfma_f32_16x16x32_bf16 v[116:119], v[196:199], v[228:231], v[116:119]
	v_mfma_f32_16x16x32_bf16 v[108:111], v[172:175], v[236:239], v[108:111]
	v_mfma_f32_16x16x32_bf16 v[100:103], v[196:199], v[236:239], v[100:103]
	v_mfma_f32_16x16x32_bf16 v[92:95], v[172:175], v[244:247], v[92:95]
	v_mfma_f32_16x16x32_bf16 v[84:87], v[196:199], v[244:247], v[84:87]
	v_mfma_f32_16x16x32_bf16 v[120:123], v[200:203], v[216:219], v[120:123]
	v_mfma_f32_16x16x32_bf16 v[112:115], v[208:211], v[216:219], v[112:115]
	v_mfma_f32_16x16x32_bf16 v[104:107], v[200:203], v[224:227], v[104:107]
	v_mfma_f32_16x16x32_bf16 v[96:99], v[208:211], v[224:227], v[96:99]
	v_mfma_f32_16x16x32_bf16 v[88:91], v[200:203], v[232:235], v[88:91]
	v_mfma_f32_16x16x32_bf16 v[80:83], v[208:211], v[232:235], v[80:83]
	v_mfma_f32_16x16x32_bf16 v[76:79], v[200:203], v[240:243], v[76:79]
	v_mfma_f32_16x16x32_bf16 v[72:75], v[208:211], v[240:243], v[72:75]
	v_mfma_f32_16x16x32_bf16 v[120:123], v[204:207], v[220:223], v[120:123]
	v_mfma_f32_16x16x32_bf16 v[112:115], v[212:215], v[220:223], v[112:115]
	v_mfma_f32_16x16x32_bf16 v[104:107], v[204:207], v[228:231], v[104:107]
	v_mfma_f32_16x16x32_bf16 v[96:99], v[212:215], v[228:231], v[96:99]
	v_mfma_f32_16x16x32_bf16 v[88:91], v[204:207], v[236:239], v[88:91]
	v_mfma_f32_16x16x32_bf16 v[80:83], v[212:215], v[236:239], v[80:83]
	v_mfma_f32_16x16x32_bf16 v[76:79], v[204:207], v[244:247], v[76:79]
	v_mfma_f32_16x16x32_bf16 v[72:75], v[212:215], v[244:247], v[72:75]
	s_barrier
	s_add_i32 s24, s26, s81
	v_lshl_add_u64 v[142:143], v[154:155], 0, s[60:61]
	s_mov_b32 m0, s24
	ds_read_b128 v[216:219], v161 offset:49152
	ds_read_b128 v[220:223], v161 offset:50176
	ds_read_b128 v[224:227], v161 offset:51200
	ds_read_b128 v[228:231], v161 offset:52224
	ds_read_b128 v[232:235], v161 offset:53248
	ds_read_b128 v[236:239], v161 offset:54272
	ds_read_b128 v[240:243], v161 offset:55296
	ds_read_b128 v[244:247], v161 offset:56320
	global_load_lds_dwordx4 v[142:143], off
	v_lshl_add_u64 v[142:143], v[162:163], 0, s[60:61]
	s_add_i32 m0, s24, 0x2000
	s_add_i32 s24, s28, s81
	global_load_lds_dwordx4 v[142:143], off
	v_lshl_add_u64 v[142:143], v[168:169], 0, s[60:61]
	s_mov_b32 m0, s24
	v_lshl_add_u64 v[140:141], v[140:141], 0, s[60:61]
	global_load_lds_dwordx4 v[142:143], off
	v_lshl_add_u64 v[142:143], v[176:177], 0, s[60:61]
	s_add_i32 m0, s24, 0x2000
	s_nop 0
	global_load_lds_dwordx4 v[142:143], off
	v_lshl_add_u64 v[142:143], v[248:249], 0, s[60:61]
	s_mov_b32 m0, s27
	s_nop 0
	global_load_lds_dwordx4 v[142:143], off
	s_mov_b32 m0, s44
	s_nop 0
	global_load_lds_dwordx4 v[140:141], off
	s_waitcnt vmcnt(8)
	s_waitcnt lgkmcnt(0)
	s_barrier
	s_waitcnt lgkmcnt(0)
	v_mfma_f32_16x16x32_bf16 v[68:71], v[136:139], v[216:219], v[68:71]
	v_mfma_f32_16x16x32_bf16 v[64:67], v[192:195], v[216:219], v[64:67]
	v_mfma_f32_16x16x32_bf16 v[60:63], v[136:139], v[224:227], v[60:63]
	v_mfma_f32_16x16x32_bf16 v[52:55], v[192:195], v[224:227], v[52:55]
	v_mfma_f32_16x16x32_bf16 v[44:47], v[136:139], v[232:235], v[44:47]
	v_mfma_f32_16x16x32_bf16 v[28:31], v[192:195], v[232:235], v[28:31]
	v_mfma_f32_16x16x32_bf16 v[20:23], v[136:139], v[240:243], v[20:23]
	v_mfma_f32_16x16x32_bf16 v[12:15], v[192:195], v[240:243], v[12:15]
	v_mfma_f32_16x16x32_bf16 v[68:71], v[172:175], v[220:223], v[68:71]
	v_mfma_f32_16x16x32_bf16 v[64:67], v[196:199], v[220:223], v[64:67]
	v_mfma_f32_16x16x32_bf16 v[60:63], v[172:175], v[228:231], v[60:63]
	v_mfma_f32_16x16x32_bf16 v[52:55], v[196:199], v[228:231], v[52:55]
	v_mfma_f32_16x16x32_bf16 v[44:47], v[172:175], v[236:239], v[44:47]
	v_mfma_f32_16x16x32_bf16 v[28:31], v[196:199], v[236:239], v[28:31]
	v_mfma_f32_16x16x32_bf16 v[20:23], v[172:175], v[244:247], v[20:23]
	v_mfma_f32_16x16x32_bf16 v[12:15], v[196:199], v[244:247], v[12:15]
	v_mfma_f32_16x16x32_bf16 v[56:59], v[200:203], v[216:219], v[56:59]
	v_mfma_f32_16x16x32_bf16 v[48:51], v[208:211], v[216:219], v[48:51]
	v_mfma_f32_16x16x32_bf16 v[40:43], v[200:203], v[224:227], v[40:43]
	v_mfma_f32_16x16x32_bf16 v[24:27], v[208:211], v[224:227], v[24:27]
	v_mfma_f32_16x16x32_bf16 v[16:19], v[200:203], v[232:235], v[16:19]
	v_mfma_f32_16x16x32_bf16 v[8:11], v[208:211], v[232:235], v[8:11]
	v_mfma_f32_16x16x32_bf16 v[4:7], v[200:203], v[240:243], v[4:7]
	v_mfma_f32_16x16x32_bf16 v[0:3], v[208:211], v[240:243], v[0:3]
	v_mfma_f32_16x16x32_bf16 v[56:59], v[204:207], v[220:223], v[56:59]
	v_mfma_f32_16x16x32_bf16 v[48:51], v[212:215], v[220:223], v[48:51]
	v_mfma_f32_16x16x32_bf16 v[40:43], v[204:207], v[228:231], v[40:43]
	v_mfma_f32_16x16x32_bf16 v[24:27], v[212:215], v[228:231], v[24:27]
	v_mfma_f32_16x16x32_bf16 v[16:19], v[204:207], v[236:239], v[16:19]
	v_mfma_f32_16x16x32_bf16 v[8:11], v[212:215], v[236:239], v[8:11]
	v_mfma_f32_16x16x32_bf16 v[4:7], v[204:207], v[244:247], v[4:7]
	v_mfma_f32_16x16x32_bf16 v[0:3], v[212:215], v[244:247], v[0:3]
	s_barrier
	s_add_u32 s0, s0, 0x100
	s_addc_u32 s1, s1, 0
	s_add_u32 s70, s70, 0x100
	s_addc_u32 s71, s71, 0
	s_cmp_ge_u32 vcc_lo, s22
	s_mov_b32 s24, vcc_lo
	s_cbranch_scc0 .LBB0_899
	s_setprio 0
	s_and_b64 vcc, exec, s[34:35]
	s_cbranch_vccz .LBB0_902
	s_barrier
